# MLA DMA loop: DMA issue placed in the post-QK MFMA wait slot, precomputed LDS bases, redundant max canonicalisation dropped
# speedup vs baseline: 1.0341x; 1.0125x over previous
.Ldma_sdone_2:
	v_lshrrev_b32_e32 v207, 2, v163
	v_lshrrev_b32_e32 v201, 3, v163
	v_xor_b32_e32 v207, v207, v201
	v_and_b32_e32 v207, 1, v207
	v_mul_u32_u24_e32 v207, 12, v207
	v_xor_b32_e32 v207, v163, v207
	v_mul_u32_u24_e32 v205, 0xd0, v207
	v_mul_u32_u24_e32 v206, 0x90, v163
	v_add_u32_e32 v206, 0x3400, v206
	v_add_u32_e32 v206, v206, v170
	v_add_u32_e32 v207, v205, v170
	v_add_u32_e32 v210, s67, v207
	v_add_u32_e32 v211, s67, v206
	s_mov_b32 m0, s60
	s_nop 0
	global_load_lds_dwordx4 v202, s[18:19]
	s_mov_b32 m0, s61
	s_nop 0
	global_load_lds_dwordx4 v203, s[18:19]
	s_mov_b32 m0, s66
	s_nop 0
	global_load_lds_dwordx4 v204, s[18:19]
	v_add_u32_e32 v202, v196, v202
	v_add_u32_e32 v203, v197, v203
	v_add_u32_e32 v204, v198, v204
	s_add_u32 m0, s60, 0x5800
	s_nop 0
	global_load_lds_dwordx4 v202, s[18:19]
	s_add_u32 m0, s61, 0x5800
	s_nop 0
	global_load_lds_dwordx4 v203, s[18:19]
	s_add_u32 m0, s66, 0x5800
	s_nop 0
	global_load_lds_dwordx4 v204, s[18:19]
	v_add_u32_e32 v202, v196, v202
	v_add_u32_e32 v203, v197, v203
	v_add_u32_e32 v204, v198, v204
	s_add_u32 m0, s60, 0xb000
	s_nop 0
	global_load_lds_dwordx4 v202, s[18:19]
	s_add_u32 m0, s61, 0xb000
	s_nop 0
	global_load_lds_dwordx4 v203, s[18:19]
	s_add_u32 m0, s66, 0xb000
	s_nop 0
	global_load_lds_dwordx4 v204, s[18:19]
	v_add_u32_e32 v202, v196, v202
	v_add_u32_e32 v203, v197, v203
	v_add_u32_e32 v204, v198, v204
	s_mov_b32 s13, 0
	s_waitcnt vmcnt(6)
	s_barrier
	s_branch .Ldma_top
.Ldma_top:
	s_mov_b32 s44, s13
	s_cmp_gt_i32 s44, s12
	s_cbranch_scc1 .Ldma_skip_0
	ds_read_b128 v[50:53], v207
	ds_read_b128 v[130:133], v207 offset:32
	ds_read_b128 v[134:137], v207 offset:6656
	ds_read_b128 v[138:141], v207 offset:6688
	ds_read_b128 v[142:145], v207 offset:64
	ds_read_b128 v[146:149], v207 offset:96
	ds_read_b128 v[150:153], v207 offset:6720
	ds_read_b128 v[154:157], v207 offset:6752
	ds_read_b128 v[158:161], v207 offset:128
	ds_read_b128 v[182:185], v207 offset:160
	ds_read_b128 v[186:189], v207 offset:6784
	ds_read_b128 v[190:193], v207 offset:6816
	s_waitcnt lgkmcnt(11)
	v_mfma_f32_32x32x16_bf16 v[66:81], v[50:53], v[82:85], v[34:49]
	s_waitcnt lgkmcnt(9)
	v_mfma_f32_32x32x16_bf16 v[50:65], v[134:137], v[82:85], v[34:49]
	v_mfma_f32_32x32x16_bf16 v[66:81], v[130:133], v[90:93], v[66:81]
	s_waitcnt lgkmcnt(8)
	v_mfma_f32_32x32x16_bf16 v[50:65], v[138:141], v[90:93], v[50:65]
	s_waitcnt lgkmcnt(7)
	v_mfma_f32_32x32x16_bf16 v[66:81], v[142:145], v[94:97], v[66:81]
	s_waitcnt lgkmcnt(5)
	v_mfma_f32_32x32x16_bf16 v[50:65], v[150:153], v[94:97], v[50:65]
	v_mfma_f32_32x32x16_bf16 v[66:81], v[146:149], v[98:101], v[66:81]
	s_waitcnt lgkmcnt(4)
	v_mfma_f32_32x32x16_bf16 v[50:65], v[154:157], v[98:101], v[50:65]
	ds_read_b128 v[154:157], v206
	ds_read_b128 v[146:149], v206 offset:32
	s_waitcnt lgkmcnt(5)
	v_mfma_f32_32x32x16_bf16 v[66:81], v[158:161], v[106:109], v[66:81]
	ds_read_b128 v[158:161], v206 offset:4608
	ds_read_b128 v[150:153], v206 offset:4640
	ds_read_b128 v[142:145], v206 offset:64
	ds_read_b128 v[138:141], v206 offset:4672
	ds_read_b128 v[134:137], v206 offset:96
	ds_read_b128 v[130:133], v206 offset:4704
	s_waitcnt lgkmcnt(9)
	v_mfma_f32_32x32x16_bf16 v[50:65], v[186:189], v[106:109], v[50:65]
	v_mfma_f32_32x32x16_bf16 v[66:81], v[182:185], v[110:113], v[66:81]
	s_waitcnt lgkmcnt(8)
	v_mfma_f32_32x32x16_bf16 v[50:65], v[190:193], v[110:113], v[50:65]
	s_add_u32 m0, s60, 0x10800
	s_nop 0
	global_load_lds_dwordx4 v202, s[18:19]
	s_add_u32 m0, s61, 0x10800
	s_nop 0
	global_load_lds_dwordx4 v203, s[18:19]
	s_add_u32 m0, s66, 0x10800
	s_nop 0
	global_load_lds_dwordx4 v204, s[18:19]
	s_add_i32 s45, s13, 4
	s_cmp_lt_u32 s45, s7
	s_cbranch_scc0 .Ldma_noadv_0a
	v_add_u32_e32 v202, v196, v202
	v_add_u32_e32 v203, v197, v203
	v_add_u32_e32 v204, v198, v204
.Ldma_noadv_0a:
	v_max_f32_e32 v0, v66, v67
	v_max3_f32 v182, v68, v69, v51
	v_max3_f32 v0, v0, v50, v52
	v_max3_f32 v0, v0, v53, v70
	v_max3_f32 v182, v182, v72, v73
	v_max3_f32 v0, v0, v71, v54
	v_max3_f32 v182, v182, v56, v57
	v_max3_f32 v0, v0, v55, v74
	v_max3_f32 v182, v182, v76, v77
	v_max3_f32 v0, v0, v75, v58
	v_max3_f32 v182, v182, v60, v61
	v_max3_f32 v0, v0, v59, v78
	v_max3_f32 v182, v182, v80, v81
	v_max3_f32 v0, v0, v79, v62
	v_max3_f32 v182, v182, v64, v65
	v_max3_f32 v0, v0, v63, v182
	v_mov_b32_e32 v182, v0
	s_nop 1
	v_permlane32_swap_b32_e32 v0, v182
	v_max_f32_e32 v0, v0, v182
	v_cmp_lt_f32_e32 vcc, 0x41000000, v0
	s_cbranch_vccz .Ldma_join_0
	v_max_f32_e32 v0, v0, v0
	v_max_f32_e32 v34, 0, v0
	v_exp_f32_e64 v0, -v34
	v_add_f32_e32 v180, v180, v34
	v_sub_f32_e32 v66, v66, v34
	v_sub_f32_e32 v67, v67, v34
	v_sub_f32_e32 v68, v68, v34
	v_sub_f32_e32 v69, v69, v34
	v_sub_f32_e32 v70, v70, v34
	v_sub_f32_e32 v71, v71, v34
	v_sub_f32_e32 v72, v72, v34
	v_sub_f32_e32 v73, v73, v34
	v_sub_f32_e32 v74, v74, v34
	v_sub_f32_e32 v75, v75, v34
	v_sub_f32_e32 v76, v76, v34
	v_sub_f32_e32 v77, v77, v34
	v_sub_f32_e32 v78, v78, v34
	v_sub_f32_e32 v79, v79, v34
	v_sub_f32_e32 v80, v80, v34
	v_sub_f32_e32 v81, v81, v34
	v_sub_f32_e32 v50, v50, v34
	v_sub_f32_e32 v51, v51, v34
	v_sub_f32_e32 v52, v52, v34
	v_sub_f32_e32 v53, v53, v34
	v_sub_f32_e32 v54, v54, v34
	v_sub_f32_e32 v55, v55, v34
	v_sub_f32_e32 v56, v56, v34
	v_sub_f32_e32 v57, v57, v34
	v_sub_f32_e32 v58, v58, v34
	v_sub_f32_e32 v59, v59, v34
	v_sub_f32_e32 v60, v60, v34
	v_sub_f32_e32 v61, v61, v34
	v_sub_f32_e32 v62, v62, v34
	v_sub_f32_e32 v63, v63, v34
	v_sub_f32_e32 v64, v64, v34
	v_sub_f32_e32 v65, v65, v34
	v_sub_f32_e32 v34, 0, v180
	v_pk_mul_f32 v[32:33], v[32:33], v[0:1] op_sel_hi:[1,0]
	v_pk_mul_f32 v[30:31], v[30:31], v[0:1] op_sel_hi:[1,0]
	v_pk_mul_f32 v[28:29], v[28:29], v[0:1] op_sel_hi:[1,0]
	v_pk_mul_f32 v[26:27], v[26:27], v[0:1] op_sel_hi:[1,0]
	v_pk_mul_f32 v[24:25], v[24:25], v[0:1] op_sel_hi:[1,0]
	v_pk_mul_f32 v[22:23], v[22:23], v[0:1] op_sel_hi:[1,0]
	v_pk_mul_f32 v[20:21], v[20:21], v[0:1] op_sel_hi:[1,0]
	v_pk_mul_f32 v[18:19], v[18:19], v[0:1] op_sel_hi:[1,0]
	v_pk_mul_f32 v[16:17], v[16:17], v[0:1] op_sel_hi:[1,0]
	v_pk_mul_f32 v[14:15], v[14:15], v[0:1] op_sel_hi:[1,0]
	v_pk_mul_f32 v[12:13], v[12:13], v[0:1] op_sel_hi:[1,0]
	v_pk_mul_f32 v[10:11], v[10:11], v[0:1] op_sel_hi:[1,0]
	v_pk_mul_f32 v[8:9], v[8:9], v[0:1] op_sel_hi:[1,0]
	v_pk_mul_f32 v[6:7], v[6:7], v[0:1] op_sel_hi:[1,0]
	v_pk_mul_f32 v[4:5], v[4:5], v[0:1] op_sel_hi:[1,0]
	v_pk_mul_f32 v[2:3], v[2:3], v[0:1] op_sel_hi:[1,0]
	v_pk_mul_f32 v[172:173], v[172:173], v[0:1] op_sel_hi:[1,0]
	v_mov_b32_e32 v35, v34
	v_mov_b32_e32 v36, v34
	v_mov_b32_e32 v37, v34
	v_mov_b32_e32 v38, v34
	v_mov_b32_e32 v39, v34
	v_mov_b32_e32 v40, v34
	v_mov_b32_e32 v41, v34
	v_mov_b32_e32 v42, v34
	v_mov_b32_e32 v43, v34
	v_mov_b32_e32 v44, v34
	v_mov_b32_e32 v45, v34
	v_mov_b32_e32 v46, v34
	v_mov_b32_e32 v47, v34
	v_mov_b32_e32 v48, v34
	v_mov_b32_e32 v49, v34
.Ldma_join_0:
	v_exp_f32_e32 v182, v66
	v_exp_f32_e32 v183, v67
	v_exp_f32_e32 v184, v68
	v_exp_f32_e32 v185, v69
	v_exp_f32_e32 v70, v70
	v_exp_f32_e32 v71, v71
	v_exp_f32_e32 v72, v72
	v_exp_f32_e32 v73, v73
	v_cvt_pk_bf16_f32 v66, v182, v183
	v_cvt_pk_bf16_f32 v67, v184, v185
	v_cvt_pk_bf16_f32 v68, v70, v71
	v_cvt_pk_bf16_f32 v69, v72, v73
	s_waitcnt lgkmcnt(7)
	s_nop 0
	v_mfma_f32_32x32x16_bf16 v[18:33], v[154:157], v[66:69], v[18:33]
	s_waitcnt lgkmcnt(5)
	v_mfma_f32_32x32x16_bf16 v[2:17], v[158:161], v[66:69], v[2:17]
	v_exp_f32_e32 v66, v74
	v_exp_f32_e32 v67, v75
	v_exp_f32_e32 v74, v78
	v_exp_f32_e32 v75, v79
	v_pk_add_f32 v[78:79], v[182:183], v[172:173]
	v_exp_f32_e32 v68, v76
	v_exp_f32_e32 v69, v77
	v_exp_f32_e32 v76, v80
	v_exp_f32_e32 v77, v81
	v_pk_add_f32 v[78:79], v[184:185], v[78:79]
	s_nop 0
	v_pk_add_f32 v[70:71], v[70:71], v[78:79]
	s_nop 0
	v_pk_add_f32 v[70:71], v[72:73], v[70:71]
	s_nop 0
	v_pk_add_f32 v[70:71], v[66:67], v[70:71]
	v_cvt_pk_bf16_f32 v66, v66, v67
	v_pk_add_f32 v[70:71], v[68:69], v[70:71]
	v_cvt_pk_bf16_f32 v67, v68, v69
	v_cvt_pk_bf16_f32 v68, v74, v75
	v_cvt_pk_bf16_f32 v69, v76, v77
	s_nop 1
	v_mfma_f32_32x32x16_bf16 v[18:33], v[146:149], v[66:69], v[18:33]
	s_waitcnt lgkmcnt(4)
	v_mfma_f32_32x32x16_bf16 v[2:17], v[150:153], v[66:69], v[2:17]
	v_exp_f32_e32 v66, v50
	v_exp_f32_e32 v67, v51
	v_exp_f32_e32 v68, v52
	v_exp_f32_e32 v69, v53
	v_exp_f32_e32 v54, v54
	v_exp_f32_e32 v55, v55
	v_exp_f32_e32 v56, v56
	v_exp_f32_e32 v57, v57
	v_cvt_pk_bf16_f32 v50, v66, v67
	v_cvt_pk_bf16_f32 v51, v68, v69
	v_cvt_pk_bf16_f32 v52, v54, v55
	v_cvt_pk_bf16_f32 v53, v56, v57
	s_waitcnt lgkmcnt(3)
	s_nop 0
	v_mfma_f32_32x32x16_bf16 v[18:33], v[142:145], v[50:53], v[18:33]
	s_waitcnt lgkmcnt(2)
	v_mfma_f32_32x32x16_bf16 v[2:17], v[138:141], v[50:53], v[2:17]
	v_exp_f32_e32 v50, v58
	v_exp_f32_e32 v51, v59
	v_exp_f32_e32 v58, v62
	v_exp_f32_e32 v59, v63
	v_pk_add_f32 v[62:63], v[74:75], v[70:71]
	v_exp_f32_e32 v52, v60
	v_pk_add_f32 v[62:63], v[76:77], v[62:63]
	v_exp_f32_e32 v53, v61
	v_pk_add_f32 v[62:63], v[66:67], v[62:63]
	v_exp_f32_e32 v60, v64
	v_pk_add_f32 v[62:63], v[68:69], v[62:63]
	v_exp_f32_e32 v61, v65
	v_pk_add_f32 v[54:55], v[54:55], v[62:63]
	s_nop 0
	v_pk_add_f32 v[54:55], v[56:57], v[54:55]
	s_nop 0
	v_pk_add_f32 v[54:55], v[50:51], v[54:55]
	v_cvt_pk_bf16_f32 v50, v50, v51
	v_pk_add_f32 v[54:55], v[52:53], v[54:55]
	v_cvt_pk_bf16_f32 v51, v52, v53
	v_pk_add_f32 v[54:55], v[58:59], v[54:55]
	v_cvt_pk_bf16_f32 v52, v58, v59
	v_pk_add_f32 v[172:173], v[60:61], v[54:55]
	v_cvt_pk_bf16_f32 v53, v60, v61
	s_waitcnt lgkmcnt(1)
	s_nop 0
	v_mfma_f32_32x32x16_bf16 v[18:33], v[134:137], v[50:53], v[18:33]
	s_waitcnt lgkmcnt(0)
	v_mfma_f32_32x32x16_bf16 v[2:17], v[130:133], v[50:53], v[2:17]
	s_branch .Ldma_end_0
.Ldma_skip_0:
	s_add_u32 m0, s60, 0x10800
	s_nop 0
	global_load_lds_dwordx4 v202, s[18:19]
	s_add_u32 m0, s61, 0x10800
	s_nop 0
	global_load_lds_dwordx4 v203, s[18:19]
	s_add_u32 m0, s66, 0x10800
	s_nop 0
	global_load_lds_dwordx4 v204, s[18:19]
	s_add_i32 s45, s13, 4
	s_cmp_lt_u32 s45, s7
	s_cbranch_scc0 .Ldma_noadv_0b
	v_add_u32_e32 v202, v196, v202
	v_add_u32_e32 v203, v197, v203
	v_add_u32_e32 v204, v198, v204
.Ldma_noadv_0b:
.Ldma_end_0:
	s_waitcnt vmcnt(6)
	s_barrier
	s_add_i32 s44, s13, 1
	s_cmp_gt_i32 s44, s12
	s_cbranch_scc1 .Ldma_skip_1
	ds_read_b128 v[50:53], v207 offset:22528
	ds_read_b128 v[130:133], v207 offset:22560
	ds_read_b128 v[134:137], v207 offset:29184
	ds_read_b128 v[138:141], v207 offset:29216
	ds_read_b128 v[142:145], v207 offset:22592
	ds_read_b128 v[146:149], v207 offset:22624
	ds_read_b128 v[150:153], v207 offset:29248
	ds_read_b128 v[154:157], v207 offset:29280
	ds_read_b128 v[158:161], v207 offset:22656
	ds_read_b128 v[182:185], v207 offset:22688
	ds_read_b128 v[186:189], v207 offset:29312
	ds_read_b128 v[190:193], v207 offset:29344
	s_waitcnt lgkmcnt(11)
	v_mfma_f32_32x32x16_bf16 v[66:81], v[50:53], v[82:85], v[34:49]
	s_waitcnt lgkmcnt(9)
	v_mfma_f32_32x32x16_bf16 v[50:65], v[134:137], v[82:85], v[34:49]
	v_mfma_f32_32x32x16_bf16 v[66:81], v[130:133], v[90:93], v[66:81]
	s_waitcnt lgkmcnt(8)
	v_mfma_f32_32x32x16_bf16 v[50:65], v[138:141], v[90:93], v[50:65]
	s_waitcnt lgkmcnt(7)
	v_mfma_f32_32x32x16_bf16 v[66:81], v[142:145], v[94:97], v[66:81]
	s_waitcnt lgkmcnt(5)
	v_mfma_f32_32x32x16_bf16 v[50:65], v[150:153], v[94:97], v[50:65]
	v_mfma_f32_32x32x16_bf16 v[66:81], v[146:149], v[98:101], v[66:81]
	s_waitcnt lgkmcnt(4)
	v_mfma_f32_32x32x16_bf16 v[50:65], v[154:157], v[98:101], v[50:65]
	ds_read_b128 v[154:157], v206 offset:22528
	ds_read_b128 v[146:149], v206 offset:22560
	s_waitcnt lgkmcnt(5)
	v_mfma_f32_32x32x16_bf16 v[66:81], v[158:161], v[106:109], v[66:81]
	ds_read_b128 v[158:161], v206 offset:27136
	ds_read_b128 v[150:153], v206 offset:27168
	ds_read_b128 v[142:145], v206 offset:22592
	ds_read_b128 v[138:141], v206 offset:27200
	ds_read_b128 v[134:137], v206 offset:22624
	ds_read_b128 v[130:133], v206 offset:27232
	s_waitcnt lgkmcnt(9)
	v_mfma_f32_32x32x16_bf16 v[50:65], v[186:189], v[106:109], v[50:65]
	v_mfma_f32_32x32x16_bf16 v[66:81], v[182:185], v[110:113], v[66:81]
	s_waitcnt lgkmcnt(8)
	v_mfma_f32_32x32x16_bf16 v[50:65], v[190:193], v[110:113], v[50:65]
	s_mov_b32 m0, s60
	s_nop 0
	global_load_lds_dwordx4 v202, s[18:19]
	s_mov_b32 m0, s61
	s_nop 0
	global_load_lds_dwordx4 v203, s[18:19]
	s_mov_b32 m0, s66
	s_nop 0
	global_load_lds_dwordx4 v204, s[18:19]
	s_add_i32 s45, s13, 5
	s_cmp_lt_u32 s45, s7
	s_cbranch_scc0 .Ldma_noadv_1a
	v_add_u32_e32 v202, v196, v202
	v_add_u32_e32 v203, v197, v203
	v_add_u32_e32 v204, v198, v204

.Ldma_skip_1:
	s_mov_b32 m0, s60
	s_nop 0
	global_load_lds_dwordx4 v202, s[18:19]
	s_mov_b32 m0, s61
	s_nop 0
	global_load_lds_dwordx4 v203, s[18:19]
	s_mov_b32 m0, s66
	s_nop 0
	global_load_lds_dwordx4 v204, s[18:19]
	s_add_i32 s45, s13, 5
	s_cmp_lt_u32 s45, s7
	s_cbranch_scc0 .Ldma_noadv_1b
	v_add_u32_e32 v202, v196, v202
	v_add_u32_e32 v203, v197, v203
	v_add_u32_e32 v204, v198, v204
.Ldma_noadv_1b:
.Ldma_end_1:
	s_waitcnt vmcnt(6)
	s_barrier
	s_add_i32 s44, s13, 2
	s_cmp_gt_i32 s44, s12
	s_cbranch_scc1 .Ldma_skip_2
	ds_read_b128 v[50:53], v210
	ds_read_b128 v[130:133], v210 offset:32
	ds_read_b128 v[134:137], v210 offset:6656
	ds_read_b128 v[138:141], v210 offset:6688
	ds_read_b128 v[142:145], v210 offset:64
	ds_read_b128 v[146:149], v210 offset:96
	ds_read_b128 v[150:153], v210 offset:6720
	ds_read_b128 v[154:157], v210 offset:6752
	ds_read_b128 v[158:161], v210 offset:128
	ds_read_b128 v[182:185], v210 offset:160
	ds_read_b128 v[186:189], v210 offset:6784
	ds_read_b128 v[190:193], v210 offset:6816
	s_waitcnt lgkmcnt(11)
	v_mfma_f32_32x32x16_bf16 v[66:81], v[50:53], v[82:85], v[34:49]
	s_waitcnt lgkmcnt(9)
	v_mfma_f32_32x32x16_bf16 v[50:65], v[134:137], v[82:85], v[34:49]
	v_mfma_f32_32x32x16_bf16 v[66:81], v[130:133], v[90:93], v[66:81]
	s_waitcnt lgkmcnt(8)
	v_mfma_f32_32x32x16_bf16 v[50:65], v[138:141], v[90:93], v[50:65]
	s_waitcnt lgkmcnt(7)
	v_mfma_f32_32x32x16_bf16 v[66:81], v[142:145], v[94:97], v[66:81]
	s_waitcnt lgkmcnt(5)
	v_mfma_f32_32x32x16_bf16 v[50:65], v[150:153], v[94:97], v[50:65]
	v_mfma_f32_32x32x16_bf16 v[66:81], v[146:149], v[98:101], v[66:81]
	s_waitcnt lgkmcnt(4)
	v_mfma_f32_32x32x16_bf16 v[50:65], v[154:157], v[98:101], v[50:65]
	ds_read_b128 v[154:157], v211
	ds_read_b128 v[146:149], v211 offset:32
	s_waitcnt lgkmcnt(5)
	v_mfma_f32_32x32x16_bf16 v[66:81], v[158:161], v[106:109], v[66:81]
	ds_read_b128 v[158:161], v211 offset:4608
	ds_read_b128 v[150:153], v211 offset:4640
	ds_read_b128 v[142:145], v211 offset:64
	ds_read_b128 v[138:141], v211 offset:4672
	ds_read_b128 v[134:137], v211 offset:96
	ds_read_b128 v[130:133], v211 offset:4704
	s_waitcnt lgkmcnt(9)
	v_mfma_f32_32x32x16_bf16 v[50:65], v[186:189], v[106:109], v[50:65]
	v_mfma_f32_32x32x16_bf16 v[66:81], v[182:185], v[110:113], v[66:81]
	s_waitcnt lgkmcnt(8)
	v_mfma_f32_32x32x16_bf16 v[50:65], v[190:193], v[110:113], v[50:65]
	s_add_u32 m0, s60, 0x5800
	s_nop 0
	global_load_lds_dwordx4 v202, s[18:19]
	s_add_u32 m0, s61, 0x5800
	s_nop 0
	global_load_lds_dwordx4 v203, s[18:19]
	s_add_u32 m0, s66, 0x5800
	s_nop 0
	global_load_lds_dwordx4 v204, s[18:19]
	s_add_i32 s45, s13, 6
	s_cmp_lt_u32 s45, s7
	s_cbranch_scc0 .Ldma_noadv_2a
	v_add_u32_e32 v202, v196, v202
	v_add_u32_e32 v203, v197, v203
	v_add_u32_e32 v204, v198, v204

.Ldma_skip_2:
	s_add_u32 m0, s60, 0x5800
	s_nop 0
	global_load_lds_dwordx4 v202, s[18:19]
	s_add_u32 m0, s61, 0x5800
	s_nop 0
	global_load_lds_dwordx4 v203, s[18:19]
	s_add_u32 m0, s66, 0x5800
	s_nop 0
	global_load_lds_dwordx4 v204, s[18:19]
	s_add_i32 s45, s13, 6
	s_cmp_lt_u32 s45, s7
	s_cbranch_scc0 .Ldma_noadv_2b
	v_add_u32_e32 v202, v196, v202
	v_add_u32_e32 v203, v197, v203
	v_add_u32_e32 v204, v198, v204
.Ldma_noadv_2b:
.Ldma_end_2:
	s_waitcnt vmcnt(6)
	s_barrier
	s_add_i32 s44, s13, 3
	s_cmp_gt_i32 s44, s12
	s_cbranch_scc1 .Ldma_skip_3
	ds_read_b128 v[50:53], v210 offset:22528
	ds_read_b128 v[130:133], v210 offset:22560
	ds_read_b128 v[134:137], v210 offset:29184
	ds_read_b128 v[138:141], v210 offset:29216
	ds_read_b128 v[142:145], v210 offset:22592
	ds_read_b128 v[146:149], v210 offset:22624
	ds_read_b128 v[150:153], v210 offset:29248
	ds_read_b128 v[154:157], v210 offset:29280
	ds_read_b128 v[158:161], v210 offset:22656
	ds_read_b128 v[182:185], v210 offset:22688
	ds_read_b128 v[186:189], v210 offset:29312
	ds_read_b128 v[190:193], v210 offset:29344
	s_waitcnt lgkmcnt(11)
	v_mfma_f32_32x32x16_bf16 v[66:81], v[50:53], v[82:85], v[34:49]
	s_waitcnt lgkmcnt(9)
	v_mfma_f32_32x32x16_bf16 v[50:65], v[134:137], v[82:85], v[34:49]
	v_mfma_f32_32x32x16_bf16 v[66:81], v[130:133], v[90:93], v[66:81]
	s_waitcnt lgkmcnt(8)
	v_mfma_f32_32x32x16_bf16 v[50:65], v[138:141], v[90:93], v[50:65]
	s_waitcnt lgkmcnt(7)
	v_mfma_f32_32x32x16_bf16 v[66:81], v[142:145], v[94:97], v[66:81]
	s_waitcnt lgkmcnt(5)
	v_mfma_f32_32x32x16_bf16 v[50:65], v[150:153], v[94:97], v[50:65]
	v_mfma_f32_32x32x16_bf16 v[66:81], v[146:149], v[98:101], v[66:81]
	s_waitcnt lgkmcnt(4)
	v_mfma_f32_32x32x16_bf16 v[50:65], v[154:157], v[98:101], v[50:65]
	ds_read_b128 v[154:157], v211 offset:22528
	ds_read_b128 v[146:149], v211 offset:22560
	s_waitcnt lgkmcnt(5)
	v_mfma_f32_32x32x16_bf16 v[66:81], v[158:161], v[106:109], v[66:81]
	ds_read_b128 v[158:161], v211 offset:27136
	ds_read_b128 v[150:153], v211 offset:27168
	ds_read_b128 v[142:145], v211 offset:22592
	ds_read_b128 v[138:141], v211 offset:27200
	ds_read_b128 v[134:137], v211 offset:22624
	ds_read_b128 v[130:133], v211 offset:27232
	s_waitcnt lgkmcnt(9)
	v_mfma_f32_32x32x16_bf16 v[50:65], v[186:189], v[106:109], v[50:65]
	v_mfma_f32_32x32x16_bf16 v[66:81], v[182:185], v[110:113], v[66:81]
	s_waitcnt lgkmcnt(8)
	v_mfma_f32_32x32x16_bf16 v[50:65], v[190:193], v[110:113], v[50:65]
	s_add_u32 m0, s60, 0xb000
	s_nop 0
	global_load_lds_dwordx4 v202, s[18:19]
	s_add_u32 m0, s61, 0xb000
	s_nop 0
	global_load_lds_dwordx4 v203, s[18:19]
	s_add_u32 m0, s66, 0xb000
	s_nop 0
	global_load_lds_dwordx4 v204, s[18:19]
	s_add_i32 s45, s13, 7
	s_cmp_lt_u32 s45, s7
	s_cbranch_scc0 .Ldma_noadv_3a
	v_add_u32_e32 v202, v196, v202
	v_add_u32_e32 v203, v197, v203
	v_add_u32_e32 v204, v198, v204

.Ldma_skip_3:
	s_add_u32 m0, s60, 0xb000
	s_nop 0
	global_load_lds_dwordx4 v202, s[18:19]
	s_add_u32 m0, s61, 0xb000
	s_nop 0
	global_load_lds_dwordx4 v203, s[18:19]
	s_add_u32 m0, s66, 0xb000
	s_nop 0
	global_load_lds_dwordx4 v204, s[18:19]
	s_add_i32 s45, s13, 7
	s_cmp_lt_u32 s45, s7
	s_cbranch_scc0 .Ldma_noadv_3b
	v_add_u32_e32 v202, v196, v202
	v_add_u32_e32 v203, v197, v203
	v_add_u32_e32 v204, v198, v204
.Ldma_noadv_3b:
.Ldma_end_3:
	s_waitcnt vmcnt(6)
	s_barrier
	s_add_i32 s13, s13, 4
	s_cmp_lt_u32 s13, s7
	s_cbranch_scc1 .Ldma_top
	s_waitcnt vmcnt(0)
	s_barrier
	s_branch .LBB0_966
